# row-panel group barrier (4 workgroups) instead of the grid barrier after W_out (both layers) and after FF1 of layer 1
# speedup vs baseline: 1.0124x; 1.0039x over previous
.Lrp_done:
	s_cmp_eq_u32 s14, 11
	s_cbranch_scc1 .LBB0_681
	s_cmp_ge_i32 s17, s15
	s_cbranch_scc1 .LBB0_681
	v_readlane_b32 s99, v255, 59
	s_lshr_b32 s98, 0x140100, s14
	s_and_b32 s98, s98, s99
	s_bitcmp1_b32 s98, 0
	s_cbranch_scc0 .Lgg_no
	s_waitcnt vmcnt(0)
	s_barrier
	s_and_saveexec_b64 s[2:3], s[86:87]
	s_cbranch_execz .Lgg_join
	v_readlane_b32 s6, v253, 55
	s_and_b32 s7, s6, 7
	s_lshl_b32 s7, s7, 3
	s_bfe_u32 s6, s6, 0x30003
	s_add_i32 s6, s6, s7
	s_lshl_b32 s6, s6, 8
	s_add_i32 s6, s6, 0x4040
	s_cmp_eq_u32 s14, 18
	s_cselect_b32 s7, 4, 0
	s_cmp_eq_u32 s14, 20
	s_cselect_b32 s7, 8, s7
	s_add_i32 s6, s6, s7
	v_mov_b32_e32 v20, s6
	s_mov_b32 s58, 0
	global_atomic_add v20, v202, s[12:13]
.Lgg_spin:
	global_load_dword v22, v20, s[12:13] sc1
	s_waitcnt vmcnt(0)
	v_cmp_gt_u32_e32 vcc, 4, v22
	s_cbranch_vccz .Lgg_done
	s_sleep 1
	s_add_i32 s58, s58, 1
	s_cmp_lt_u32 s58, 0x40001
	s_cbranch_scc1 .Lgg_spin
.Lgg_done:
	buffer_inv sc1
	s_waitcnt vmcnt(0)
.Lgg_join:
	s_or_b64 exec, exec, s[2:3]
	s_barrier
	s_branch .LBB0_681
.Lgg_no:
	v_readlane_b32 s2, v253, 13
	v_readlane_b32 s3, v253, 14
	s_andn2_b64 vcc, exec, s[2:3]
	s_cbranch_vccnz .LBB0_634
	s_waitcnt vmcnt(0)
	s_barrier
	s_mov_b64 s[2:3], exec
	v_readlane_b32 s4, v253, 53
	v_readlane_b32 s5, v253, 54
	s_and_b64 s[4:5], s[2:3], s[4:5]
	s_mov_b64 exec, s[4:5]
	s_cbranch_execz .LBB0_633
	v_readlane_b32 s4, v253, 1
	v_readlane_b32 s5, v253, 2
	buffer_wbl2 sc1
	s_load_dwordx2 s[4:5], s[4:5], 0x58
	s_mov_b64 s[6:7], exec
	v_mbcnt_lo_u32_b32 v1, s6, 0
	v_mbcnt_hi_u32_b32 v1, s7, v1
	v_cmp_eq_u32_e32 vcc, 0, v1
	s_waitcnt lgkmcnt(0)
	global_load_dword v0, v65, s[4:5] offset:40
	s_and_saveexec_b64 s[8:9], vcc
	s_cbranch_execz .LBB0_626
	s_bcnt1_i32_b64 s6, s[6:7]
	v_mov_b32_e32 v2, s6
	global_atomic_add v2, v65, v2, s[4:5] offset:32 sc0
